# speedup vs baseline: 1.0447x; 1.0001x over previous
; __device__ __forceinline__ void final_phase(const bf16* xb, float* out, const float* gain, int gw, int NGW, int lane) {
;     ...
;     for (int m = gw; m < T; m += 4 * NGW) {
;         v2u v[4][4];
; #pragma unroll
;         for (int q = 0; q < 4; ++q) { const int mm = m + q * NGW < T ? m + q * NGW : m; const v2u* xr = (const v2u*)(xb + (size_t)mm * D) + lane;
; #pragma unroll
;             for (int j = 0; j < 4; ++j) v[q][j] = xr[64 * j]; }
; #pragma unroll
;         for (int q = 0; q < 4; ++q) { const int mm = m + q * NGW; if (mm >= T) break;
;             f32x4 f[4]; float s = 0.f;
; #pragma unroll
;             for (int j = 0; j < 4; ++j) { f[j] = (f32x4){bflo(v[q][j].x), bfhi(v[q][j].x), bflo(v[q][j].y), bfhi(v[q][j].y)}; s += (f[j].x * f[j].x + f[j].y * f[j].y) + (f[j].z * f[j].z + f[j].w * f[j].w); }
;             s = wave_sum(s);
;             const float rs = rsqrtf(s * (1.0f / D) + RMS_EPS);
;             f32x4* xw = (f32x4*)(out + (size_t)mm * D) + lane;
; #pragma unroll
;             for (int j = 0; j < 4; ++j) __builtin_nontemporal_store(f[j] * rs * gv[j], xw + 64 * j); }
.LBB0_16:
	s_add_i32 s2, s40, s21
	s_cmp_lt_i32 s2, 0x8000
	s_cselect_b32 s10, s2, s40
	s_ashr_i32 s11, s10, 31
	v_readlane_b32 s3, v253, 58
	s_lshl_b64 s[10:11], s[10:11], 11
	s_add_i32 s28, s3, s40
	s_cmp_lt_i32 s28, 0x8000
	s_cselect_b64 s[38:39], -1, 0
	s_and_b64 s[16:17], s[38:39], exec
	s_cselect_b32 s16, s28, s40
	s_ashr_i32 s17, s16, 31
	s_mul_i32 s3, s8, 24
	s_lshl_b64 s[16:17], s[16:17], 11
	s_add_i32 s22, s3, s40
	s_cmp_lt_i32 s22, 0x8000
	s_cselect_b64 s[24:25], -1, 0
	s_and_b64 s[42:43], s[24:25], exec
	s_cselect_b32 s42, s22, s40
	s_ashr_i32 s41, s40, 31
	s_lshl_b64 s[44:45], s[40:41], 11
	s_waitcnt vmcnt(4)
	v_lshl_add_u64 v[22:23], v[0:1], 0, s[44:45]
	global_load_dwordx2 v[52:53], v[22:23], off
	global_load_dwordx2 v[54:55], v[22:23], off offset:512
	global_load_dwordx2 v[56:57], v[22:23], off offset:1024
	global_load_dwordx2 v[58:59], v[22:23], off offset:1536
	v_lshl_add_u64 v[22:23], v[0:1], 0, s[10:11]
	s_ashr_i32 s43, s42, 31
	global_load_dwordx2 v[44:45], v[22:23], off
	global_load_dwordx2 v[42:43], v[22:23], off offset:512
	global_load_dwordx2 v[40:41], v[22:23], off offset:1024
	global_load_dwordx2 v[38:39], v[22:23], off offset:1536
	v_lshl_add_u64 v[22:23], v[0:1], 0, s[16:17]
	s_lshl_b64 s[10:11], s[42:43], 11
	global_load_dwordx2 v[36:37], v[22:23], off
	global_load_dwordx2 v[34:35], v[22:23], off offset:512
	global_load_dwordx2 v[32:33], v[22:23], off offset:1024
	global_load_dwordx2 v[30:31], v[22:23], off offset:1536
	v_lshl_add_u64 v[22:23], v[0:1], 0, s[10:11]
	global_load_dwordx2 v[28:29], v[22:23], off
	global_load_dwordx2 v[26:27], v[22:23], off offset:512
	global_load_dwordx2 v[24:25], v[22:23], off offset:1024
	s_nop 0
	global_load_dwordx2 v[22:23], v[22:23], off offset:1536
	s_lshl_b64 s[10:11], s[40:41], 12
	s_cmpk_gt_i32 s2, 0x7fff
	s_waitcnt vmcnt(15)
	v_lshlrev_b32_e32 v61, 16, v53
	v_lshlrev_b32_e32 v60, 16, v52
	v_and_b32_e32 v53, 0xffff0000, v53
	v_and_b32_e32 v52, 0xffff0000, v52
	s_waitcnt vmcnt(14)
	v_lshlrev_b32_e32 v63, 16, v55
	v_lshlrev_b32_e32 v62, 16, v54
	v_and_b32_e32 v55, 0xffff0000, v55
	v_and_b32_e32 v54, 0xffff0000, v54
	s_waitcnt vmcnt(13)
	v_lshlrev_b32_e32 v64, 16, v56
	v_and_b32_e32 v65, 0xffff0000, v56
	v_lshlrev_b32_e32 v56, 16, v57
	s_waitcnt vmcnt(12)
	v_lshlrev_b32_e32 v66, 16, v58
	v_pk_mul_f32 v[68:69], v[52:53], v[52:53]
	v_pk_mul_f32 v[70:71], v[54:55], v[54:55]
	v_and_b32_e32 v57, 0xffff0000, v57
	v_mul_f32_e32 v67, v64, v64
	v_mul_f32_e32 v73, v65, v65
	v_mul_f32_e32 v74, v56, v56
	v_mov_b32_e32 v72, v66
	v_pk_fma_f32 v[68:69], v[60:61], v[60:61], v[68:69]
	v_pk_fma_f32 v[70:71], v[62:63], v[62:63], v[70:71]
	v_and_b32_e32 v51, 0xffff0000, v58
	v_lshlrev_b32_e32 v58, 16, v59
	v_and_b32_e32 v59, 0xffff0000, v59
	v_pk_fma_f32 v[74:75], v[56:57], v[56:57], v[74:75] op_sel_hi:[1,1,0]
	v_pk_add_f32 v[72:73], v[66:67], v[72:73]
	v_pk_add_f32 v[68:69], v[68:69], v[68:69] op_sel_hi:[0,1]
	v_pk_add_f32 v[70:71], v[70:71], v[70:71] op_sel_hi:[0,1]
	v_mul_f32_e32 v76, v66, v66
	v_mul_f32_e32 v74, v51, v51
	v_mov_b32_e32 v77, v73
	v_mul_f32_e32 v70, v58, v58
	v_mul_f32_e32 v68, v59, v59
	v_pk_add_f32 v[72:73], v[76:77], v[74:75]
	v_pk_add_f32 v[68:69], v[70:71], v[68:69]
	v_mov_b32_e32 v71, v52
	v_pk_add_f32 v[68:69], v[72:73], v[68:69]
	v_mov_b32_e32 v52, v61
	v_add_f32_e32 v67, v68, v69
	ds_bpermute_b32 v68, v2, v67
	s_waitcnt lgkmcnt(0)
	v_add_f32_e32 v67, v67, v68
	ds_bpermute_b32 v68, v46, v67
	s_waitcnt lgkmcnt(0)
	v_add_f32_e32 v67, v67, v68
	ds_bpermute_b32 v68, v47, v67
	s_waitcnt lgkmcnt(0)
	v_add_f32_e32 v67, v67, v68
	ds_bpermute_b32 v68, v48, v67
	s_waitcnt lgkmcnt(0)
	v_add_f32_e32 v67, v67, v68
	ds_bpermute_b32 v70, v49, v67
	v_lshl_add_u64 v[68:69], v[20:21], 0, s[10:11]
	s_waitcnt lgkmcnt(0)
	v_add_f32_e32 v67, v67, v70
	ds_bpermute_b32 v72, v50, v67
	v_mov_b32_e32 v70, v60
	v_mov_b32_e32 v60, v62
	s_waitcnt lgkmcnt(0)
	v_add_f32_e32 v61, v67, v72
	v_fmamk_f32 v61, v61, 0x3a800000, v217
	v_mul_f32_e32 v62, 0x4b800000, v61
	v_cmp_gt_f32_e32 vcc, s33, v61
	v_mov_b32_e32 v67, v51
	s_nop 0
	v_cndmask_b32_e32 v61, v61, v62, vcc
	v_rsq_f32_e32 v62, v61
	v_mov_b32_e32 v61, v54
	v_mov_b32_e32 v54, v63
	v_mul_f32_e32 v51, 0x45800000, v62
	v_cndmask_b32_e32 v62, v62, v51, vcc
	v_pk_mul_f32 v[70:71], v[62:63], v[70:71] op_sel_hi:[0,1]
	v_pk_mul_f32 v[52:53], v[62:63], v[52:53] op_sel_hi:[0,1]
	v_pk_mul_f32 v[60:61], v[62:63], v[60:61] op_sel_hi:[0,1]
	v_pk_mul_f32 v[72:73], v[62:63], v[54:55] op_sel_hi:[0,1]
	v_pk_mul_f32 v[64:65], v[64:65], v[62:63] op_sel_hi:[1,0]
	v_pk_mul_f32 v[74:75], v[56:57], v[62:63] op_sel_hi:[1,0]
	v_pk_mul_f32 v[76:77], v[66:67], v[62:63] op_sel_hi:[1,0]
	v_pk_mul_f32 v[66:67], v[58:59], v[62:63] op_sel_hi:[1,0]
	v_pk_mul_f32 v[54:55], v[6:7], v[52:53]
	v_pk_mul_f32 v[52:53], v[4:5], v[70:71]
	v_pk_mul_f32 v[58:59], v[10:11], v[72:73]
	v_pk_mul_f32 v[56:57], v[8:9], v[60:61]
	v_pk_mul_f32 v[62:63], v[14:15], v[74:75]
	v_pk_mul_f32 v[60:61], v[12:13], v[64:65]
	v_pk_mul_f32 v[66:67], v[18:19], v[66:67]
	v_pk_mul_f32 v[64:65], v[16:17], v[76:77]
	global_store_dwordx4 v[68:69], v[52:55], off sc0 sc1 nt
	global_store_dwordx4 v[68:69], v[56:59], off offset:1024 sc0 sc1 nt
	global_store_dwordx4 v[68:69], v[60:63], off offset:2048 sc0 sc1 nt
	global_store_dwordx4 v[68:69], v[64:67], off offset:3072 sc0 sc1 nt
	s_cbranch_scc1 .LBB0_15
; __device__ __forceinline__ void final_phase(const bf16* xb, float* out, const float* gain, int gw, int NGW, int lane) {
;     ...
;     for (int m = gw; m < T; m += 4 * NGW) {
;         v2u v[4][4];
; #pragma unroll
;         for (int q = 0; q < 4; ++q) { const int mm = m + q * NGW < T ? m + q * NGW : m; const v2u* xr = (const v2u*)(xb + (size_t)mm * D) + lane;
; #pragma unroll
;             for (int j = 0; j < 4; ++j) v[q][j] = xr[64 * j]; }
; #pragma unroll
;         for (int q = 0; q < 4; ++q) { const int mm = m + q * NGW; if (mm >= T) break;
;             f32x4 f[4]; float s = 0.f;
; #pragma unroll
;             for (int j = 0; j < 4; ++j) { f[j] = (f32x4){bflo(v[q][j].x), bfhi(v[q][j].x), bflo(v[q][j].y), bfhi(v[q][j].y)}; s += (f[j].x * f[j].x + f[j].y * f[j].y) + (f[j].z * f[j].z + f[j].w * f[j].w); }
;             s = wave_sum(s);
;             const float rs = rsqrtf(s * (1.0f / D) + RMS_EPS);
;             f32x4* xw = (f32x4*)(out + (size_t)mm * D) + lane;
; #pragma unroll
;             for (int j = 0; j < 4; ++j) __builtin_nontemporal_store(f[j] * rs * gv[j], xw + 64 * j); }
	s_waitcnt vmcnt(15)
	v_lshlrev_b32_e32 v52, 16, v44
	v_and_b32_e32 v53, 0xffff0000, v44
	v_lshlrev_b32_e32 v44, 16, v45
	v_and_b32_e32 v45, 0xffff0000, v45
	v_mul_f32_e32 v54, v45, v45
	s_waitcnt vmcnt(12)
	v_lshlrev_b32_e32 v65, 16, v38
	v_and_b32_e32 v67, 0xffff0000, v38
	v_mul_f32_e32 v38, v53, v53
	v_pk_fma_f32 v[54:55], v[44:45], v[44:45], v[54:55] op_sel_hi:[1,1,0]
	v_lshlrev_b32_e32 v57, 16, v43
	v_lshlrev_b32_e32 v56, 16, v42
	v_and_b32_e32 v43, 0xffff0000, v43
	v_and_b32_e32 v42, 0xffff0000, v42
	v_lshlrev_b32_e32 v68, 16, v39
	v_and_b32_e32 v69, 0xffff0000, v39
	v_pk_fma_f32 v[38:39], v[52:53], v[52:53], v[38:39] op_sel_hi:[1,1,0]
	v_pk_mul_f32 v[58:59], v[42:43], v[42:43]
	v_lshlrev_b32_e32 v60, 16, v40
	v_and_b32_e32 v61, 0xffff0000, v40
	v_lshlrev_b32_e32 v62, 16, v41
	v_and_b32_e32 v63, 0xffff0000, v41
	v_mov_b32_e32 v64, v38
	v_mov_b32_e32 v40, v54
	v_mov_b32_e32 v41, v65
	v_pk_fma_f32 v[58:59], v[56:57], v[56:57], v[58:59]
	v_pk_add_f32 v[38:39], v[38:39], v[54:55]
	v_pk_mul_f32 v[40:41], v[64:65], v[40:41]
	v_mul_f32_e32 v51, v67, v67
	v_mov_b32_e32 v39, v41
	v_pk_add_f32 v[40:41], v[58:59], v[58:59] op_sel:[0,1] op_sel_hi:[1,0]
	v_mul_f32_e32 v54, v63, v63
	v_mov_b32_e32 v41, v51
	v_pk_add_f32 v[38:39], v[38:39], v[40:41]
	v_mul_f32_e32 v40, v61, v61
	v_mul_f32_e32 v66, v68, v68
	v_mul_f32_e32 v70, v69, v69
	v_pk_fma_f32 v[40:41], v[60:61], v[60:61], v[40:41] op_sel_hi:[1,1,0]
	v_pk_fma_f32 v[54:55], v[62:63], v[62:63], v[54:55] op_sel_hi:[1,1,0]
	v_mov_b32_e32 v41, v66
	v_mov_b32_e32 v55, v70
	v_pk_add_f32 v[40:41], v[40:41], v[54:55]
	s_ashr_i32 s3, s2, 31
	v_pk_add_f32 v[38:39], v[38:39], v[40:41]
	s_lshl_b64 s[10:11], s[2:3], 12
	v_add_f32_e32 v38, v38, v39
	ds_bpermute_b32 v39, v2, v38
	v_lshl_add_u64 v[58:59], v[20:21], 0, s[10:11]
	v_mov_b32_e32 v66, v65
	s_waitcnt lgkmcnt(0)
	v_add_f32_e32 v38, v38, v39
	ds_bpermute_b32 v39, v46, v38
	s_waitcnt lgkmcnt(0)
	v_add_f32_e32 v38, v38, v39
	ds_bpermute_b32 v39, v47, v38
	s_waitcnt lgkmcnt(0)
	v_add_f32_e32 v38, v38, v39
	ds_bpermute_b32 v39, v48, v38
	s_waitcnt lgkmcnt(0)
	v_add_f32_e32 v38, v38, v39
	ds_bpermute_b32 v39, v49, v38
	s_waitcnt lgkmcnt(0)
	v_add_f32_e32 v38, v38, v39
	ds_bpermute_b32 v39, v50, v38
	s_waitcnt lgkmcnt(0)
	v_add_f32_e32 v38, v38, v39
	v_fmamk_f32 v38, v38, 0x3a800000, v217
	v_mul_f32_e32 v39, 0x4b800000, v38
	v_cmp_gt_f32_e32 vcc, s33, v38
	s_nop 1
	v_cndmask_b32_e32 v38, v38, v39, vcc
	v_rsq_f32_e32 v38, v38
	s_nop 0
	v_mul_f32_e32 v39, 0x45800000, v38
	v_cndmask_b32_e32 v54, v38, v39, vcc
	v_pk_mul_f32 v[38:39], v[54:55], v[52:53] op_sel_hi:[0,1]
	v_pk_mul_f32 v[40:41], v[54:55], v[44:45] op_sel_hi:[0,1]
	v_pk_mul_f32 v[40:41], v[6:7], v[40:41]
	v_pk_mul_f32 v[38:39], v[4:5], v[38:39]
	global_store_dwordx4 v[58:59], v[38:41], off sc0 sc1 nt
	s_andn2_b64 vcc, exec, s[38:39]
	s_nop 0
	v_mov_b32_e32 v38, v56
	v_mov_b32_e32 v39, v42
	v_mov_b32_e32 v42, v57
	v_pk_mul_f32 v[38:39], v[54:55], v[38:39] op_sel_hi:[0,1]
	v_pk_mul_f32 v[40:41], v[54:55], v[42:43] op_sel_hi:[0,1]
	v_pk_mul_f32 v[40:41], v[10:11], v[40:41]
	v_pk_mul_f32 v[38:39], v[8:9], v[38:39]
	global_store_dwordx4 v[58:59], v[38:41], off offset:1024 sc0 sc1 nt
	s_nop 1
	v_pk_mul_f32 v[38:39], v[54:55], v[60:61] op_sel_hi:[0,1]
	v_pk_mul_f32 v[40:41], v[54:55], v[62:63] op_sel_hi:[0,1]
	v_pk_mul_f32 v[40:41], v[14:15], v[40:41]
	v_pk_mul_f32 v[38:39], v[12:13], v[38:39]
	global_store_dwordx4 v[58:59], v[38:41], off offset:2048 sc0 sc1 nt
	s_nop 1
	v_pk_mul_f32 v[38:39], v[66:67], v[54:55] op_sel_hi:[1,0]
	v_pk_mul_f32 v[40:41], v[68:69], v[54:55] op_sel_hi:[1,0]
	v_pk_mul_f32 v[38:39], v[16:17], v[38:39]
	v_pk_mul_f32 v[40:41], v[18:19], v[40:41]
	global_store_dwordx4 v[58:59], v[38:41], off offset:3072 sc0 sc1 nt
	s_cbranch_vccnz .LBB0_15
	s_waitcnt vmcnt(15)
	v_lshlrev_b32_e32 v38, 16, v36
	v_and_b32_e32 v39, 0xffff0000, v36
	v_lshlrev_b32_e32 v36, 16, v37
	v_and_b32_e32 v37, 0xffff0000, v37
	v_mul_f32_e32 v40, v37, v37
	s_waitcnt vmcnt(12)
	v_lshlrev_b32_e32 v57, 16, v30
	v_and_b32_e32 v59, 0xffff0000, v30
	v_mul_f32_e32 v30, v39, v39
	v_pk_fma_f32 v[40:41], v[36:37], v[36:37], v[40:41] op_sel_hi:[1,1,0]
	v_lshlrev_b32_e32 v43, 16, v35
	v_lshlrev_b32_e32 v42, 16, v34
	v_and_b32_e32 v35, 0xffff0000, v35
	v_and_b32_e32 v34, 0xffff0000, v34
	v_lshlrev_b32_e32 v60, 16, v31
	v_and_b32_e32 v61, 0xffff0000, v31
	v_pk_fma_f32 v[30:31], v[38:39], v[38:39], v[30:31] op_sel_hi:[1,1,0]
	v_pk_mul_f32 v[44:45], v[34:35], v[34:35]
	v_lshlrev_b32_e32 v52, 16, v32
	v_and_b32_e32 v53, 0xffff0000, v32
	v_lshlrev_b32_e32 v54, 16, v33
	v_and_b32_e32 v55, 0xffff0000, v33
	v_mov_b32_e32 v56, v30
	v_mov_b32_e32 v32, v40
	v_mov_b32_e32 v33, v57
	v_pk_fma_f32 v[44:45], v[42:43], v[42:43], v[44:45]
	v_pk_add_f32 v[30:31], v[30:31], v[40:41]
	v_pk_mul_f32 v[32:33], v[56:57], v[32:33]
	v_mul_f32_e32 v51, v59, v59
	v_mov_b32_e32 v31, v33
	v_pk_add_f32 v[32:33], v[44:45], v[44:45] op_sel:[0,1] op_sel_hi:[1,0]
	v_mul_f32_e32 v40, v55, v55
	v_mov_b32_e32 v33, v51
	v_pk_add_f32 v[30:31], v[30:31], v[32:33]
	v_mul_f32_e32 v32, v53, v53
	v_mul_f32_e32 v58, v60, v60
	v_mul_f32_e32 v62, v61, v61
	v_pk_fma_f32 v[32:33], v[52:53], v[52:53], v[32:33] op_sel_hi:[1,1,0]
	v_pk_fma_f32 v[40:41], v[54:55], v[54:55], v[40:41] op_sel_hi:[1,1,0]
	v_mov_b32_e32 v33, v58
	v_mov_b32_e32 v41, v62
	v_pk_add_f32 v[32:33], v[32:33], v[40:41]
	s_ashr_i32 s29, s28, 31
	v_pk_add_f32 v[30:31], v[30:31], v[32:33]
	s_lshl_b64 s[10:11], s[28:29], 12
	v_add_f32_e32 v30, v30, v31
	ds_bpermute_b32 v31, v2, v30
	v_lshl_add_u64 v[44:45], v[20:21], 0, s[10:11]
	v_mov_b32_e32 v58, v57
	s_waitcnt lgkmcnt(0)
; __device__ __forceinline__ void final_phase(const bf16* xb, float* out, const float* gain, int gw, int NGW, int lane) {
;     ...
;     for (int m = gw; m < T; m += 4 * NGW) {
;         v2u v[4][4];
; #pragma unroll
;         for (int q = 0; q < 4; ++q) { const int mm = m + q * NGW < T ? m + q * NGW : m; const v2u* xr = (const v2u*)(xb + (size_t)mm * D) + lane;
; #pragma unroll
;             for (int j = 0; j < 4; ++j) v[q][j] = xr[64 * j]; }
; #pragma unroll
;         for (int q = 0; q < 4; ++q) { const int mm = m + q * NGW; if (mm >= T) break;
;             f32x4 f[4]; float s = 0.f;
; #pragma unroll
;             for (int j = 0; j < 4; ++j) { f[j] = (f32x4){bflo(v[q][j].x), bfhi(v[q][j].x), bflo(v[q][j].y), bfhi(v[q][j].y)}; s += (f[j].x * f[j].x + f[j].y * f[j].y) + (f[j].z * f[j].z + f[j].w * f[j].w); }
;             s = wave_sum(s);
;             const float rs = rsqrtf(s * (1.0f / D) + RMS_EPS);
;             f32x4* xw = (f32x4*)(out + (size_t)mm * D) + lane;
; #pragma unroll
;             for (int j = 0; j < 4; ++j) __builtin_nontemporal_store(f[j] * rs * gv[j], xw + 64 * j); }
	v_add_f32_e32 v30, v30, v31
	ds_bpermute_b32 v31, v46, v30
	s_waitcnt lgkmcnt(0)
	v_add_f32_e32 v30, v30, v31
	ds_bpermute_b32 v31, v47, v30
	s_waitcnt lgkmcnt(0)
	v_add_f32_e32 v30, v30, v31
	ds_bpermute_b32 v31, v48, v30
	s_waitcnt lgkmcnt(0)
	v_add_f32_e32 v30, v30, v31
	ds_bpermute_b32 v31, v49, v30
	s_waitcnt lgkmcnt(0)
	v_add_f32_e32 v30, v30, v31
	ds_bpermute_b32 v31, v50, v30
	s_waitcnt lgkmcnt(0)
	v_add_f32_e32 v30, v30, v31
	v_fmamk_f32 v30, v30, 0x3a800000, v217
	v_mul_f32_e32 v31, 0x4b800000, v30
	v_cmp_gt_f32_e32 vcc, s33, v30
	s_nop 1
	v_cndmask_b32_e32 v30, v30, v31, vcc
	v_rsq_f32_e32 v30, v30
	s_nop 0
	v_mul_f32_e32 v31, 0x45800000, v30
	v_cndmask_b32_e32 v40, v30, v31, vcc
	v_pk_mul_f32 v[30:31], v[40:41], v[38:39] op_sel_hi:[0,1]
	v_pk_mul_f32 v[32:33], v[40:41], v[36:37] op_sel_hi:[0,1]
	v_pk_mul_f32 v[32:33], v[6:7], v[32:33]
	v_pk_mul_f32 v[30:31], v[4:5], v[30:31]
	global_store_dwordx4 v[44:45], v[30:33], off sc0 sc1 nt
	s_andn2_b64 vcc, exec, s[24:25]
	s_nop 0
	v_mov_b32_e32 v30, v42
	v_mov_b32_e32 v31, v34
	v_mov_b32_e32 v34, v43
	v_pk_mul_f32 v[30:31], v[40:41], v[30:31] op_sel_hi:[0,1]
	v_pk_mul_f32 v[32:33], v[40:41], v[34:35] op_sel_hi:[0,1]
	v_pk_mul_f32 v[32:33], v[10:11], v[32:33]
	v_pk_mul_f32 v[30:31], v[8:9], v[30:31]
	global_store_dwordx4 v[44:45], v[30:33], off offset:1024 sc0 sc1 nt
	s_nop 1
	v_pk_mul_f32 v[30:31], v[40:41], v[52:53] op_sel_hi:[0,1]
	v_pk_mul_f32 v[32:33], v[40:41], v[54:55] op_sel_hi:[0,1]
	v_pk_mul_f32 v[32:33], v[14:15], v[32:33]
	v_pk_mul_f32 v[30:31], v[12:13], v[30:31]
	global_store_dwordx4 v[44:45], v[30:33], off offset:2048 sc0 sc1 nt
	s_nop 1
	v_pk_mul_f32 v[30:31], v[58:59], v[40:41] op_sel_hi:[1,0]
	v_pk_mul_f32 v[32:33], v[60:61], v[40:41] op_sel_hi:[1,0]
	v_pk_mul_f32 v[30:31], v[16:17], v[30:31]
	v_pk_mul_f32 v[32:33], v[18:19], v[32:33]
	global_store_dwordx4 v[44:45], v[30:33], off offset:3072 sc0 sc1 nt
	s_cbranch_vccnz .LBB0_15
	s_waitcnt vmcnt(15)
	v_lshlrev_b32_e32 v30, 16, v28
	v_and_b32_e32 v31, 0xffff0000, v28
	v_lshlrev_b32_e32 v28, 16, v29
	v_and_b32_e32 v29, 0xffff0000, v29
	v_mul_f32_e32 v32, v29, v29
	s_waitcnt vmcnt(12)
	v_lshlrev_b32_e32 v43, 16, v22
	v_and_b32_e32 v45, 0xffff0000, v22
	v_mul_f32_e32 v22, v31, v31
	v_pk_fma_f32 v[32:33], v[28:29], v[28:29], v[32:33] op_sel_hi:[1,1,0]
	v_lshlrev_b32_e32 v35, 16, v27
	v_lshlrev_b32_e32 v34, 16, v26
	v_and_b32_e32 v27, 0xffff0000, v27
	v_and_b32_e32 v26, 0xffff0000, v26
	v_lshlrev_b32_e32 v52, 16, v23
	v_and_b32_e32 v53, 0xffff0000, v23
	v_pk_fma_f32 v[22:23], v[30:31], v[30:31], v[22:23] op_sel_hi:[1,1,0]
	v_pk_mul_f32 v[36:37], v[26:27], v[26:27]
	v_lshlrev_b32_e32 v38, 16, v24
	v_and_b32_e32 v39, 0xffff0000, v24
	v_lshlrev_b32_e32 v40, 16, v25
	v_and_b32_e32 v41, 0xffff0000, v25
	v_mov_b32_e32 v42, v22
	v_mov_b32_e32 v24, v32
	v_mov_b32_e32 v25, v43
	v_pk_fma_f32 v[36:37], v[34:35], v[34:35], v[36:37]
	v_pk_add_f32 v[22:23], v[22:23], v[32:33]
	v_pk_mul_f32 v[24:25], v[42:43], v[24:25]
	v_mul_f32_e32 v44, v45, v45
	v_mov_b32_e32 v23, v25
	v_pk_add_f32 v[24:25], v[36:37], v[36:37] op_sel:[0,1] op_sel_hi:[1,0]
	v_mul_f32_e32 v32, v41, v41
	v_mov_b32_e32 v25, v44
	v_pk_add_f32 v[22:23], v[22:23], v[24:25]
	v_mul_f32_e32 v24, v39, v39
	v_mul_f32_e32 v51, v52, v52
	v_mul_f32_e32 v54, v53, v53
	v_pk_fma_f32 v[24:25], v[38:39], v[38:39], v[24:25] op_sel_hi:[1,1,0]
	v_pk_fma_f32 v[32:33], v[40:41], v[40:41], v[32:33] op_sel_hi:[1,1,0]
	v_mov_b32_e32 v25, v51
	v_mov_b32_e32 v33, v54
	v_pk_add_f32 v[24:25], v[24:25], v[32:33]
	s_ashr_i32 s23, s22, 31
	v_pk_add_f32 v[22:23], v[22:23], v[24:25]
	s_lshl_b64 s[10:11], s[22:23], 12
	v_add_f32_e32 v22, v22, v23
	ds_bpermute_b32 v23, v2, v22
	v_lshl_add_u64 v[36:37], v[20:21], 0, s[10:11]
	v_mov_b32_e32 v44, v43
	s_waitcnt lgkmcnt(0)
	v_add_f32_e32 v22, v22, v23
	ds_bpermute_b32 v23, v46, v22
	s_waitcnt lgkmcnt(0)
	v_add_f32_e32 v22, v22, v23
	ds_bpermute_b32 v23, v47, v22
	s_waitcnt lgkmcnt(0)
	v_add_f32_e32 v22, v22, v23
	ds_bpermute_b32 v23, v48, v22
	s_waitcnt lgkmcnt(0)
	v_add_f32_e32 v22, v22, v23
	ds_bpermute_b32 v23, v49, v22
	s_waitcnt lgkmcnt(0)
	v_add_f32_e32 v22, v22, v23
	ds_bpermute_b32 v23, v50, v22
	s_waitcnt lgkmcnt(0)
	v_add_f32_e32 v22, v22, v23
	v_fmamk_f32 v22, v22, 0x3a800000, v217
	v_mul_f32_e32 v23, 0x4b800000, v22
	v_cmp_gt_f32_e32 vcc, s33, v22
	s_nop 1
	v_cndmask_b32_e32 v22, v22, v23, vcc
	v_rsq_f32_e32 v22, v22
	s_nop 0
	v_mul_f32_e32 v23, 0x45800000, v22
	v_cndmask_b32_e32 v32, v22, v23, vcc
	v_pk_mul_f32 v[22:23], v[32:33], v[30:31] op_sel_hi:[0,1]
	v_pk_mul_f32 v[24:25], v[32:33], v[28:29] op_sel_hi:[0,1]
	v_pk_mul_f32 v[24:25], v[6:7], v[24:25]
	v_pk_mul_f32 v[22:23], v[4:5], v[22:23]
	global_store_dwordx4 v[36:37], v[22:25], off sc0 sc1 nt
	s_nop 1
	v_mov_b32_e32 v22, v34
	v_mov_b32_e32 v23, v26
	v_mov_b32_e32 v26, v35
	v_pk_mul_f32 v[22:23], v[32:33], v[22:23] op_sel_hi:[0,1]
	v_pk_mul_f32 v[24:25], v[32:33], v[26:27] op_sel_hi:[0,1]
	v_pk_mul_f32 v[24:25], v[10:11], v[24:25]
	v_pk_mul_f32 v[22:23], v[8:9], v[22:23]
	global_store_dwordx4 v[36:37], v[22:25], off offset:1024 sc0 sc1 nt
	s_nop 1
	v_pk_mul_f32 v[22:23], v[32:33], v[38:39] op_sel_hi:[0,1]
	v_pk_mul_f32 v[24:25], v[32:33], v[40:41] op_sel_hi:[0,1]
	v_pk_mul_f32 v[24:25], v[14:15], v[24:25]
	v_pk_mul_f32 v[22:23], v[12:13], v[22:23]
	global_store_dwordx4 v[36:37], v[22:25], off offset:2048 sc0 sc1 nt
	s_nop 1
	v_pk_mul_f32 v[22:23], v[44:45], v[32:33] op_sel_hi:[1,0]
	v_pk_mul_f32 v[24:25], v[52:53], v[32:33] op_sel_hi:[1,0]
	v_pk_mul_f32 v[22:23], v[16:17], v[22:23]
	v_pk_mul_f32 v[24:25], v[18:19], v[24:25]
	global_store_dwordx4 v[36:37], v[22:25], off offset:3072 sc0 sc1 nt
	s_branch .LBB0_15
